# attention: scalar-base stage DMAs + per-tile rendezvous moved into the PV segment (on top of v165)
# baseline (speedup 1.0000x reference)
.LBB0_1116:
	s_mov_b64 s[54:55], s[52:53]
	s_mov_b64 s[56:57], s[48:49]
	v_mov_b32_e32 v2, v0
	v_mov_b32_e32 v3, v0
	v_mov_b32_e32 v1, v0
	v_mov_b64_e32 v[22:23], v[2:3]
	v_mov_b64_e32 v[26:27], v[2:3]
	v_mov_b64_e32 v[30:31], v[2:3]
	v_mov_b64_e32 v[34:35], v[2:3]
	v_mov_b64_e32 v[38:39], v[2:3]
	v_mov_b64_e32 v[42:43], v[2:3]
	v_mov_b64_e32 v[46:47], v[2:3]
	v_mov_b64_e32 v[50:51], v[2:3]
	v_mov_b64_e32 v[54:55], v[2:3]
	v_mov_b64_e32 v[58:59], v[2:3]
	v_mov_b64_e32 v[62:63], v[2:3]
	v_mov_b64_e32 v[66:67], v[2:3]
	v_mov_b64_e32 v[70:71], v[2:3]
	v_mov_b64_e32 v[74:75], v[2:3]
	v_mov_b64_e32 v[78:79], v[2:3]
	v_mov_b64_e32 v[82:83], v[2:3]
	s_mov_b32 s91, s93
	s_mov_b32 s90, s92
	s_sub_i32 s50, 63, s87
	v_mov_b32_e32 v143, 0xf149f2ca
	v_mov_b64_e32 v[146:147], v[140:141]
	v_mov_b64_e32 v[148:149], v[138:139]
	v_mov_b64_e32 v[20:21], v[0:1]
	v_mov_b64_e32 v[24:25], v[0:1]
	v_mov_b64_e32 v[28:29], v[0:1]
	v_mov_b64_e32 v[32:33], v[0:1]
	v_mov_b64_e32 v[36:37], v[0:1]
	v_mov_b64_e32 v[40:41], v[0:1]
	v_mov_b64_e32 v[44:45], v[0:1]
	v_mov_b64_e32 v[48:49], v[0:1]
	v_mov_b64_e32 v[52:53], v[0:1]
	v_mov_b64_e32 v[56:57], v[0:1]
	v_mov_b64_e32 v[60:61], v[0:1]
	v_mov_b64_e32 v[64:65], v[0:1]
	v_mov_b64_e32 v[68:69], v[0:1]
	v_mov_b64_e32 v[72:73], v[0:1]
	v_mov_b64_e32 v[76:77], v[0:1]
	v_mov_b64_e32 v[80:81], v[0:1]
	v_mov_b32_e32 v1, 0
	s_mov_b32 s70, 0
	s_waitcnt vmcnt(0)
	s_waitcnt vmcnt(0)
	s_waitcnt lgkmcnt(0)
	s_barrier
.LBB0_1117:
	s_and_b32 s92, s70, 1
	s_add_i32 s70, s70, 1
	s_lshl_b32 s71, s92, 15
	v_add_u32_e32 v2, s71, v160
	v_add_u32_e32 v3, v2, v153
	v_add_u32_e32 v124, v2, v154
	v_add_u32_e32 v125, v2, v155
	v_add_u32_e32 v2, v2, v156
	ds_read_b128 v[84:87], v3
	ds_read_b128 v[88:91], v3 offset:2048
	ds_read_b128 v[92:95], v124
	ds_read_b128 v[96:99], v124 offset:2048
	ds_read_b128 v[100:103], v125
	ds_read_b128 v[104:107], v125 offset:2048
	ds_read_b128 v[108:111], v2
	ds_read_b128 v[112:115], v2 offset:2048
	ds_read_b128 v[116:119], v3 offset:16384
	ds_read_b128 v[166:169], v3 offset:18432
	ds_read_b128 v[120:123], v124 offset:16384
	ds_read_b128 v[170:173], v124 offset:18432
	ds_read_b128 v[174:177], v125 offset:16384
	ds_read_b128 v[178:181], v125 offset:18432
	ds_read_b128 v[182:185], v2 offset:16384
	ds_read_b128 v[186:189], v2 offset:18432
	s_cmp_lt_i32 s70, s69
	s_cbranch_scc0 .Latt_k_done
	s_xor_b32 s0, s71, 0x8000
	s_add_i32 s1, s79, s0
	s_add_u32 s54, s54, 0x40000
	s_addc_u32 s55, s55, 0
	s_mov_b32 m0, s1
	s_add_u32 s58, s54, 0x4000
	global_load_lds_dwordx4 v140, s[54:55]
	s_addc_u32 s59, s55, 0
	s_add_i32 m0, s1, 0x800
	s_nop 0
	global_load_lds_dwordx4 v140, s[58:59]
	s_add_u32 s58, s54, 0x20000
	s_addc_u32 s59, s55, 0
	s_add_i32 m0, s1, 0x4000
	s_nop 0
	global_load_lds_dwordx4 v140, s[58:59]
	s_add_u32 s58, s54, 0x24000
	s_addc_u32 s59, s55, 0
	s_add_i32 m0, s1, 0x4800
	s_nop 0
	global_load_lds_dwordx4 v140, s[58:59]

.LBB0_1126:
	v_sub_f32_e32 v128, v128, v143
	v_exp_f32_e32 v128, v128
	v_sub_f32_e32 v129, v129, v143
	v_exp_f32_e32 v129, v129
	v_sub_f32_e32 v130, v130, v143
	v_exp_f32_e32 v130, v130
	v_sub_f32_e32 v131, v131, v143
	v_exp_f32_e32 v131, v131
	v_sub_f32_e32 v124, v124, v143
	v_add_f32_e32 v165, 0, v128
	v_exp_f32_e32 v124, v124
	v_sub_f32_e32 v125, v125, v143
	v_add_f32_e32 v165, v129, v165
	v_exp_f32_e32 v125, v125
	v_sub_f32_e32 v126, v126, v143
	v_add_f32_e32 v165, v130, v165
	v_exp_f32_e32 v126, v126
	v_sub_f32_e32 v127, v127, v143
	v_add_f32_e32 v165, v131, v165
	v_exp_f32_e32 v127, v127
	v_sub_f32_e32 v120, v120, v143
	v_add_f32_e32 v165, v124, v165
	v_exp_f32_e32 v166, v120
	v_sub_f32_e32 v120, v121, v143
	v_add_f32_e32 v165, v125, v165
	v_exp_f32_e32 v167, v120
	v_sub_f32_e32 v120, v122, v143
	v_add_f32_e32 v165, v126, v165
	v_exp_f32_e32 v168, v120
	v_sub_f32_e32 v120, v123, v143
	v_add_f32_e32 v165, v127, v165
	v_exp_f32_e32 v123, v120
	v_sub_f32_e32 v116, v116, v143
	v_add_f32_e32 v120, v166, v165
	v_exp_f32_e32 v165, v116
	v_sub_f32_e32 v116, v117, v143
	v_add_f32_e32 v120, v167, v120
	v_exp_f32_e32 v117, v116
	v_sub_f32_e32 v116, v118, v143
	v_add_f32_e32 v120, v168, v120
	v_exp_f32_e32 v169, v116
	v_sub_f32_e32 v116, v119, v143
	v_add_f32_e32 v120, v123, v120
	v_exp_f32_e32 v170, v116
	v_add_f32_e32 v116, v165, v120
	v_add_f32_e32 v116, v117, v116
	v_add_f32_e32 v116, v169, v116
	v_add_f32_e32 v116, v170, v116
	v_fmac_f32_e32 v116, v1, v2
	v_cvt_pk_bf16_f32 v118, v128, v129
	v_cvt_pk_bf16_f32 v119, v130, v131
	v_cvt_pk_bf16_f32 v120, v124, v125
	v_cvt_pk_bf16_f32 v121, v126, v127
	v_cvt_pk_bf16_f32 v122, v166, v167
	v_cvt_pk_bf16_f32 v123, v168, v123
	v_cvt_pk_bf16_f32 v124, v165, v117
	v_cvt_pk_bf16_f32 v125, v169, v170
	s_waitcnt lgkmcnt(0)
	v_mfma_f32_16x16x32_bf16 v[80:83], v[100:103], v[118:121], v[80:83]
	v_mfma_f32_16x16x32_bf16 v[76:79], v[88:91], v[118:121], v[76:79]
	v_mfma_f32_16x16x32_bf16 v[72:75], v[92:95], v[118:121], v[72:75]
	v_mfma_f32_16x16x32_bf16 v[68:71], v[84:87], v[118:121], v[68:71]
	v_mfma_f32_16x16x32_bf16 v[80:83], v[112:115], v[122:125], v[80:83]
	v_mfma_f32_16x16x32_bf16 v[76:79], v[104:107], v[122:125], v[76:79]
	v_mfma_f32_16x16x32_bf16 v[72:75], v[108:111], v[122:125], v[72:75]
	v_mfma_f32_16x16x32_bf16 v[68:71], v[96:99], v[122:125], v[68:71]
	ds_read_b128 v[84:87], v3 offset:16384
	ds_read_b128 v[88:91], v3 offset:18432
	ds_read_b128 v[92:95], v145 offset:16384
	ds_read_b128 v[96:99], v145 offset:18432
	ds_read_b128 v[100:103], v3 offset:20480
	ds_read_b128 v[104:107], v3 offset:22528
	ds_read_b128 v[108:111], v145 offset:20480
	ds_read_b128 v[112:115], v145 offset:22528
	ds_read_b128 v[126:129], v3 offset:24576
	ds_read_b128 v[166:169], v3 offset:26624
	ds_read_b128 v[170:173], v145 offset:24576
	ds_read_b128 v[174:177], v145 offset:26624
	ds_read_b128 v[178:181], v3 offset:28672
	ds_read_b128 v[182:185], v3 offset:30720
	ds_read_b128 v[186:189], v145 offset:28672
	ds_read_b128 v[190:193], v145 offset:30720
	v_mfma_f32_16x16x32_bf16 v[64:67], v[194:197], v[118:121], v[64:67]
	v_mfma_f32_16x16x32_bf16 v[60:63], v[198:201], v[118:121], v[60:63]
	v_mfma_f32_16x16x32_bf16 v[56:59], v[210:213], v[118:121], v[56:59]
	v_mfma_f32_16x16x32_bf16 v[52:55], v[214:217], v[118:121], v[52:55]
	v_mfma_f32_16x16x32_bf16 v[64:67], v[202:205], v[122:125], v[64:67]
	v_mfma_f32_16x16x32_bf16 v[60:63], v[206:209], v[122:125], v[60:63]
	v_mfma_f32_16x16x32_bf16 v[56:59], v[218:221], v[122:125], v[56:59]
	v_mfma_f32_16x16x32_bf16 v[52:55], v[222:225], v[122:125], v[52:55]
	s_waitcnt vmcnt(0)
	s_waitcnt lgkmcnt(0)
	s_barrier
	v_mfma_f32_16x16x32_bf16 v[48:51], v[84:87], v[118:121], v[48:51]
	v_mfma_f32_16x16x32_bf16 v[44:47], v[88:91], v[118:121], v[44:47]
	v_mfma_f32_16x16x32_bf16 v[40:43], v[100:103], v[118:121], v[40:43]
	v_mfma_f32_16x16x32_bf16 v[36:39], v[104:107], v[118:121], v[36:39]
	v_mfma_f32_16x16x32_bf16 v[48:51], v[92:95], v[122:125], v[48:51]
	v_mfma_f32_16x16x32_bf16 v[44:47], v[96:99], v[122:125], v[44:47]
	v_mfma_f32_16x16x32_bf16 v[40:43], v[108:111], v[122:125], v[40:43]
	v_mfma_f32_16x16x32_bf16 v[36:39], v[112:115], v[122:125], v[36:39]
	s_waitcnt lgkmcnt(0)
	v_mfma_f32_16x16x32_bf16 v[32:35], v[126:129], v[118:121], v[32:35]
	v_mfma_f32_16x16x32_bf16 v[28:31], v[166:169], v[118:121], v[28:31]
	v_mfma_f32_16x16x32_bf16 v[24:27], v[178:181], v[118:121], v[24:27]
	v_mfma_f32_16x16x32_bf16 v[20:23], v[182:185], v[118:121], v[20:23]
	v_mfma_f32_16x16x32_bf16 v[32:35], v[170:173], v[122:125], v[32:35]
	v_mfma_f32_16x16x32_bf16 v[28:31], v[174:177], v[122:125], v[28:31]
	v_mfma_f32_16x16x32_bf16 v[24:27], v[186:189], v[122:125], v[24:27]
	v_mfma_f32_16x16x32_bf16 v[20:23], v[190:193], v[122:125], v[20:23]
	s_add_i32 s50, s50, 64
	s_cmp_eq_u32 s69, s70
	s_cbranch_scc1 .LBB0_1129
	v_mov_b32_e32 v1, v116
	s_branch .LBB0_1117
